# P0 mod GEMV: 9 readlanes per weight row go to distinct SGPR pairs first, so the VALU-SGPR hazard s_nops between readlane and pk_fma disappear (stacked on SALU DMA addressing + setprio cleanup)
# baseline (speedup 1.0000x reference)
.LBB0_16:
	v_add_co_u32_e32 v2, vcc, 0xffde4000, v100
	s_nop 1
	v_addc_co_u32_e32 v3, vcc, -1, v101, vcc
	v_add_co_u32_e32 v4, vcc, 0xffe08000, v100
	s_nop 1
	v_addc_co_u32_e32 v5, vcc, -1, v101, vcc
	global_load_dwordx4 v[112:115], v[2:3], off nt
	global_load_dwordx4 v[116:119], v[4:5], off nt
	v_add_co_u32_e32 v2, vcc, 0xffe2c000, v100
	s_nop 1
	v_addc_co_u32_e32 v3, vcc, -1, v101, vcc
	v_add_co_u32_e32 v4, vcc, 0xffe50000, v100
	s_nop 1
	v_addc_co_u32_e32 v5, vcc, -1, v101, vcc
	global_load_dwordx4 v[90:93], v[2:3], off nt
	global_load_dwordx4 v[86:89], v[4:5], off nt
	v_add_co_u32_e32 v2, vcc, 0xffe74000, v100
	s_nop 1
	v_addc_co_u32_e32 v3, vcc, -1, v101, vcc
	v_add_co_u32_e32 v4, vcc, 0xffe98000, v100
	s_nop 1
	v_addc_co_u32_e32 v5, vcc, -1, v101, vcc
	global_load_dwordx4 v[82:85], v[2:3], off nt
	global_load_dwordx4 v[78:81], v[4:5], off nt
	v_add_co_u32_e32 v2, vcc, 0xffebc000, v100
	s_nop 1
	v_addc_co_u32_e32 v3, vcc, -1, v101, vcc
	v_add_co_u32_e32 v4, vcc, 0xffee0000, v100
	s_nop 1
	v_addc_co_u32_e32 v5, vcc, -1, v101, vcc
	global_load_dwordx4 v[74:77], v[2:3], off nt
	global_load_dwordx4 v[70:73], v[4:5], off nt
	v_add_co_u32_e32 v2, vcc, 0xfff04000, v100
	s_nop 1
	v_addc_co_u32_e32 v3, vcc, -1, v101, vcc
	v_add_co_u32_e32 v4, vcc, 0xfff28000, v100
	s_nop 1
	v_addc_co_u32_e32 v5, vcc, -1, v101, vcc
	global_load_dwordx4 v[66:69], v[2:3], off nt
	global_load_dwordx4 v[62:65], v[4:5], off nt
	v_add_co_u32_e32 v2, vcc, 0xfff4c000, v100
	s_nop 1
	v_addc_co_u32_e32 v3, vcc, -1, v101, vcc
	v_add_co_u32_e32 v4, vcc, 0xfff70000, v100
	s_nop 1
	v_addc_co_u32_e32 v5, vcc, -1, v101, vcc
	global_load_dwordx4 v[46:49], v[2:3], off nt
	global_load_dwordx4 v[18:21], v[4:5], off nt
	v_add_co_u32_e32 v2, vcc, 0xfff94000, v100
	s_nop 1
	v_addc_co_u32_e32 v3, vcc, -1, v101, vcc
	v_add_co_u32_e32 v4, vcc, 0xfffb8000, v100
	s_nop 1
	v_addc_co_u32_e32 v5, vcc, -1, v101, vcc
	global_load_dwordx4 v[14:17], v[2:3], off nt
	global_load_dwordx4 v[10:13], v[4:5], off nt
	v_add_co_u32_e32 v2, vcc, 0xfffdc000, v100
	s_nop 1
	v_addc_co_u32_e32 v3, vcc, -1, v101, vcc
	global_load_dwordx4 v[6:9], v[2:3], off nt
	s_nop 0
	global_load_dwordx4 v[2:5], v[100:101], off nt
	v_readlane_b32 s56, v1, s6
	v_readlane_b32 s58, v104, s6
	v_readlane_b32 s60, v105, s6
	v_readlane_b32 s62, v106, s6
	v_readlane_b32 s64, v107, s6
	v_readlane_b32 s66, v108, s6
	v_readlane_b32 s68, v109, s6
	v_readlane_b32 s70, v110, s6
	v_readlane_b32 s72, v111, s6
	s_add_i32 s7, s6, 1
	s_waitcnt vmcnt(15)
	v_pk_fma_f32 v[24:25], v[114:115], s[56:57], v[24:25] op_sel_hi:[1,0,1]
	v_pk_fma_f32 v[22:23], v[112:113], s[56:57], v[22:23] op_sel_hi:[1,0,1]
	v_pk_fma_f32 v[28:29], v[114:115], s[58:59], v[28:29] op_sel_hi:[1,0,1]
	v_pk_fma_f32 v[26:27], v[112:113], s[58:59], v[26:27] op_sel_hi:[1,0,1]
	v_pk_fma_f32 v[32:33], v[114:115], s[60:61], v[32:33] op_sel_hi:[1,0,1]
	v_pk_fma_f32 v[30:31], v[112:113], s[60:61], v[30:31] op_sel_hi:[1,0,1]
	v_pk_fma_f32 v[36:37], v[114:115], s[62:63], v[36:37] op_sel_hi:[1,0,1]
	v_pk_fma_f32 v[34:35], v[112:113], s[62:63], v[34:35] op_sel_hi:[1,0,1]
	v_pk_fma_f32 v[40:41], v[114:115], s[64:65], v[40:41] op_sel_hi:[1,0,1]
	v_pk_fma_f32 v[38:39], v[112:113], s[64:65], v[38:39] op_sel_hi:[1,0,1]
	v_pk_fma_f32 v[44:45], v[114:115], s[66:67], v[44:45] op_sel_hi:[1,0,1]
	v_pk_fma_f32 v[42:43], v[112:113], s[66:67], v[42:43] op_sel_hi:[1,0,1]
	v_pk_fma_f32 v[52:53], v[114:115], s[68:69], v[52:53] op_sel_hi:[1,0,1]
	v_pk_fma_f32 v[50:51], v[112:113], s[68:69], v[50:51] op_sel_hi:[1,0,1]
	v_pk_fma_f32 v[56:57], v[114:115], s[70:71], v[56:57] op_sel_hi:[1,0,1]
	v_pk_fma_f32 v[54:55], v[112:113], s[70:71], v[54:55] op_sel_hi:[1,0,1]
	v_pk_fma_f32 v[60:61], v[114:115], s[72:73], v[60:61] op_sel_hi:[1,0,1]
	v_pk_fma_f32 v[58:59], v[112:113], s[72:73], v[58:59] op_sel_hi:[1,0,1]
	v_readlane_b32 s56, v1, s7
	v_readlane_b32 s58, v104, s7
	v_readlane_b32 s60, v105, s7
	v_readlane_b32 s62, v106, s7
	v_readlane_b32 s64, v107, s7
	v_readlane_b32 s66, v108, s7
	v_readlane_b32 s68, v109, s7
	v_readlane_b32 s70, v110, s7
	v_readlane_b32 s72, v111, s7
	s_add_i32 s7, s6, 2
	s_waitcnt vmcnt(14)
	v_pk_fma_f32 v[24:25], v[118:119], s[56:57], v[24:25] op_sel_hi:[1,0,1]
	v_pk_fma_f32 v[22:23], v[116:117], s[56:57], v[22:23] op_sel_hi:[1,0,1]
	v_pk_fma_f32 v[28:29], v[118:119], s[58:59], v[28:29] op_sel_hi:[1,0,1]
	v_pk_fma_f32 v[26:27], v[116:117], s[58:59], v[26:27] op_sel_hi:[1,0,1]
	v_pk_fma_f32 v[32:33], v[118:119], s[60:61], v[32:33] op_sel_hi:[1,0,1]
	v_pk_fma_f32 v[30:31], v[116:117], s[60:61], v[30:31] op_sel_hi:[1,0,1]
	v_pk_fma_f32 v[36:37], v[118:119], s[62:63], v[36:37] op_sel_hi:[1,0,1]
	v_pk_fma_f32 v[34:35], v[116:117], s[62:63], v[34:35] op_sel_hi:[1,0,1]
	v_pk_fma_f32 v[40:41], v[118:119], s[64:65], v[40:41] op_sel_hi:[1,0,1]
	v_pk_fma_f32 v[38:39], v[116:117], s[64:65], v[38:39] op_sel_hi:[1,0,1]
	v_pk_fma_f32 v[44:45], v[118:119], s[66:67], v[44:45] op_sel_hi:[1,0,1]
	v_pk_fma_f32 v[42:43], v[116:117], s[66:67], v[42:43] op_sel_hi:[1,0,1]
	v_pk_fma_f32 v[52:53], v[118:119], s[68:69], v[52:53] op_sel_hi:[1,0,1]
	v_pk_fma_f32 v[50:51], v[116:117], s[68:69], v[50:51] op_sel_hi:[1,0,1]
	v_pk_fma_f32 v[56:57], v[118:119], s[70:71], v[56:57] op_sel_hi:[1,0,1]
	v_pk_fma_f32 v[54:55], v[116:117], s[70:71], v[54:55] op_sel_hi:[1,0,1]
	v_pk_fma_f32 v[60:61], v[118:119], s[72:73], v[60:61] op_sel_hi:[1,0,1]
	v_pk_fma_f32 v[58:59], v[116:117], s[72:73], v[58:59] op_sel_hi:[1,0,1]
	v_readlane_b32 s56, v1, s7
	v_readlane_b32 s58, v104, s7
	v_readlane_b32 s60, v105, s7
	v_readlane_b32 s62, v106, s7
	v_readlane_b32 s64, v107, s7
	v_readlane_b32 s66, v108, s7
	v_readlane_b32 s68, v109, s7
	v_readlane_b32 s70, v110, s7
	v_readlane_b32 s72, v111, s7
	s_add_i32 s7, s6, 3
	s_waitcnt vmcnt(13)
	v_pk_fma_f32 v[24:25], v[92:93], s[56:57], v[24:25] op_sel_hi:[1,0,1]
	v_pk_fma_f32 v[22:23], v[90:91], s[56:57], v[22:23] op_sel_hi:[1,0,1]
	v_pk_fma_f32 v[28:29], v[92:93], s[58:59], v[28:29] op_sel_hi:[1,0,1]
	v_pk_fma_f32 v[26:27], v[90:91], s[58:59], v[26:27] op_sel_hi:[1,0,1]
	v_pk_fma_f32 v[32:33], v[92:93], s[60:61], v[32:33] op_sel_hi:[1,0,1]
	v_pk_fma_f32 v[30:31], v[90:91], s[60:61], v[30:31] op_sel_hi:[1,0,1]
	v_pk_fma_f32 v[36:37], v[92:93], s[62:63], v[36:37] op_sel_hi:[1,0,1]
	v_pk_fma_f32 v[34:35], v[90:91], s[62:63], v[34:35] op_sel_hi:[1,0,1]
	v_pk_fma_f32 v[40:41], v[92:93], s[64:65], v[40:41] op_sel_hi:[1,0,1]
	v_pk_fma_f32 v[38:39], v[90:91], s[64:65], v[38:39] op_sel_hi:[1,0,1]
	v_pk_fma_f32 v[44:45], v[92:93], s[66:67], v[44:45] op_sel_hi:[1,0,1]
	v_pk_fma_f32 v[42:43], v[90:91], s[66:67], v[42:43] op_sel_hi:[1,0,1]
	v_pk_fma_f32 v[52:53], v[92:93], s[68:69], v[52:53] op_sel_hi:[1,0,1]
	v_pk_fma_f32 v[50:51], v[90:91], s[68:69], v[50:51] op_sel_hi:[1,0,1]
	v_pk_fma_f32 v[56:57], v[92:93], s[70:71], v[56:57] op_sel_hi:[1,0,1]
	v_pk_fma_f32 v[54:55], v[90:91], s[70:71], v[54:55] op_sel_hi:[1,0,1]
	v_pk_fma_f32 v[60:61], v[92:93], s[72:73], v[60:61] op_sel_hi:[1,0,1]
	v_pk_fma_f32 v[58:59], v[90:91], s[72:73], v[58:59] op_sel_hi:[1,0,1]
	v_readlane_b32 s56, v1, s7
	v_readlane_b32 s58, v104, s7
	v_readlane_b32 s60, v105, s7
	v_readlane_b32 s62, v106, s7
	v_readlane_b32 s64, v107, s7
	v_readlane_b32 s66, v108, s7
	v_readlane_b32 s68, v109, s7
	v_readlane_b32 s70, v110, s7
	v_readlane_b32 s72, v111, s7
	s_add_i32 s7, s6, 4
	s_waitcnt vmcnt(12)
	v_pk_fma_f32 v[24:25], v[88:89], s[56:57], v[24:25] op_sel_hi:[1,0,1]
	v_pk_fma_f32 v[22:23], v[86:87], s[56:57], v[22:23] op_sel_hi:[1,0,1]
	v_pk_fma_f32 v[28:29], v[88:89], s[58:59], v[28:29] op_sel_hi:[1,0,1]
	v_pk_fma_f32 v[26:27], v[86:87], s[58:59], v[26:27] op_sel_hi:[1,0,1]
	v_pk_fma_f32 v[32:33], v[88:89], s[60:61], v[32:33] op_sel_hi:[1,0,1]
	v_pk_fma_f32 v[30:31], v[86:87], s[60:61], v[30:31] op_sel_hi:[1,0,1]
	v_pk_fma_f32 v[36:37], v[88:89], s[62:63], v[36:37] op_sel_hi:[1,0,1]
	v_pk_fma_f32 v[34:35], v[86:87], s[62:63], v[34:35] op_sel_hi:[1,0,1]
	v_pk_fma_f32 v[40:41], v[88:89], s[64:65], v[40:41] op_sel_hi:[1,0,1]
	v_pk_fma_f32 v[38:39], v[86:87], s[64:65], v[38:39] op_sel_hi:[1,0,1]
	v_pk_fma_f32 v[44:45], v[88:89], s[66:67], v[44:45] op_sel_hi:[1,0,1]
	v_pk_fma_f32 v[42:43], v[86:87], s[66:67], v[42:43] op_sel_hi:[1,0,1]
	v_pk_fma_f32 v[52:53], v[88:89], s[68:69], v[52:53] op_sel_hi:[1,0,1]
	v_pk_fma_f32 v[50:51], v[86:87], s[68:69], v[50:51] op_sel_hi:[1,0,1]
	v_pk_fma_f32 v[56:57], v[88:89], s[70:71], v[56:57] op_sel_hi:[1,0,1]
	v_pk_fma_f32 v[54:55], v[86:87], s[70:71], v[54:55] op_sel_hi:[1,0,1]
	v_pk_fma_f32 v[60:61], v[88:89], s[72:73], v[60:61] op_sel_hi:[1,0,1]
	v_pk_fma_f32 v[58:59], v[86:87], s[72:73], v[58:59] op_sel_hi:[1,0,1]
	v_readlane_b32 s56, v1, s7
	v_readlane_b32 s58, v104, s7
	v_readlane_b32 s60, v105, s7
	v_readlane_b32 s62, v106, s7
	v_readlane_b32 s64, v107, s7
	v_readlane_b32 s66, v108, s7
	v_readlane_b32 s68, v109, s7
	v_readlane_b32 s70, v110, s7
	v_readlane_b32 s72, v111, s7
	s_add_i32 s7, s6, 5
	s_waitcnt vmcnt(11)
	v_pk_fma_f32 v[24:25], v[84:85], s[56:57], v[24:25] op_sel_hi:[1,0,1]
	v_pk_fma_f32 v[22:23], v[82:83], s[56:57], v[22:23] op_sel_hi:[1,0,1]
	v_pk_fma_f32 v[28:29], v[84:85], s[58:59], v[28:29] op_sel_hi:[1,0,1]
	v_pk_fma_f32 v[26:27], v[82:83], s[58:59], v[26:27] op_sel_hi:[1,0,1]
	v_pk_fma_f32 v[32:33], v[84:85], s[60:61], v[32:33] op_sel_hi:[1,0,1]
	v_pk_fma_f32 v[30:31], v[82:83], s[60:61], v[30:31] op_sel_hi:[1,0,1]
	v_pk_fma_f32 v[36:37], v[84:85], s[62:63], v[36:37] op_sel_hi:[1,0,1]
	v_pk_fma_f32 v[34:35], v[82:83], s[62:63], v[34:35] op_sel_hi:[1,0,1]
	v_pk_fma_f32 v[40:41], v[84:85], s[64:65], v[40:41] op_sel_hi:[1,0,1]
	v_pk_fma_f32 v[38:39], v[82:83], s[64:65], v[38:39] op_sel_hi:[1,0,1]
	v_pk_fma_f32 v[44:45], v[84:85], s[66:67], v[44:45] op_sel_hi:[1,0,1]
	v_pk_fma_f32 v[42:43], v[82:83], s[66:67], v[42:43] op_sel_hi:[1,0,1]
	v_pk_fma_f32 v[52:53], v[84:85], s[68:69], v[52:53] op_sel_hi:[1,0,1]
	v_pk_fma_f32 v[50:51], v[82:83], s[68:69], v[50:51] op_sel_hi:[1,0,1]
	v_pk_fma_f32 v[56:57], v[84:85], s[70:71], v[56:57] op_sel_hi:[1,0,1]
	v_pk_fma_f32 v[54:55], v[82:83], s[70:71], v[54:55] op_sel_hi:[1,0,1]
	v_pk_fma_f32 v[60:61], v[84:85], s[72:73], v[60:61] op_sel_hi:[1,0,1]
	v_pk_fma_f32 v[58:59], v[82:83], s[72:73], v[58:59] op_sel_hi:[1,0,1]
	v_readlane_b32 s56, v1, s7
	v_readlane_b32 s58, v104, s7
	v_readlane_b32 s60, v105, s7
	v_readlane_b32 s62, v106, s7
	v_readlane_b32 s64, v107, s7
	v_readlane_b32 s66, v108, s7
	v_readlane_b32 s68, v109, s7
	v_readlane_b32 s70, v110, s7
	v_readlane_b32 s72, v111, s7
	s_add_i32 s7, s6, 6
	s_waitcnt vmcnt(10)
	v_pk_fma_f32 v[24:25], v[80:81], s[56:57], v[24:25] op_sel_hi:[1,0,1]
	v_pk_fma_f32 v[22:23], v[78:79], s[56:57], v[22:23] op_sel_hi:[1,0,1]
	v_pk_fma_f32 v[28:29], v[80:81], s[58:59], v[28:29] op_sel_hi:[1,0,1]
	v_pk_fma_f32 v[26:27], v[78:79], s[58:59], v[26:27] op_sel_hi:[1,0,1]
	v_pk_fma_f32 v[32:33], v[80:81], s[60:61], v[32:33] op_sel_hi:[1,0,1]
	v_pk_fma_f32 v[30:31], v[78:79], s[60:61], v[30:31] op_sel_hi:[1,0,1]
	v_pk_fma_f32 v[36:37], v[80:81], s[62:63], v[36:37] op_sel_hi:[1,0,1]
	v_pk_fma_f32 v[34:35], v[78:79], s[62:63], v[34:35] op_sel_hi:[1,0,1]
	v_pk_fma_f32 v[40:41], v[80:81], s[64:65], v[40:41] op_sel_hi:[1,0,1]
	v_pk_fma_f32 v[38:39], v[78:79], s[64:65], v[38:39] op_sel_hi:[1,0,1]
	v_pk_fma_f32 v[44:45], v[80:81], s[66:67], v[44:45] op_sel_hi:[1,0,1]
	v_pk_fma_f32 v[42:43], v[78:79], s[66:67], v[42:43] op_sel_hi:[1,0,1]
	v_pk_fma_f32 v[52:53], v[80:81], s[68:69], v[52:53] op_sel_hi:[1,0,1]
	v_pk_fma_f32 v[50:51], v[78:79], s[68:69], v[50:51] op_sel_hi:[1,0,1]
	v_pk_fma_f32 v[56:57], v[80:81], s[70:71], v[56:57] op_sel_hi:[1,0,1]
	v_pk_fma_f32 v[54:55], v[78:79], s[70:71], v[54:55] op_sel_hi:[1,0,1]
	v_pk_fma_f32 v[60:61], v[80:81], s[72:73], v[60:61] op_sel_hi:[1,0,1]
	v_pk_fma_f32 v[58:59], v[78:79], s[72:73], v[58:59] op_sel_hi:[1,0,1]
	v_readlane_b32 s56, v1, s7
	v_readlane_b32 s58, v104, s7
	v_readlane_b32 s60, v105, s7
	v_readlane_b32 s62, v106, s7
	v_readlane_b32 s64, v107, s7
	v_readlane_b32 s66, v108, s7
	v_readlane_b32 s68, v109, s7
	v_readlane_b32 s70, v110, s7
	v_readlane_b32 s72, v111, s7
	s_add_i32 s7, s6, 7
	s_waitcnt vmcnt(9)
	v_pk_fma_f32 v[24:25], v[76:77], s[56:57], v[24:25] op_sel_hi:[1,0,1]
	v_pk_fma_f32 v[22:23], v[74:75], s[56:57], v[22:23] op_sel_hi:[1,0,1]
	v_pk_fma_f32 v[28:29], v[76:77], s[58:59], v[28:29] op_sel_hi:[1,0,1]
	v_pk_fma_f32 v[26:27], v[74:75], s[58:59], v[26:27] op_sel_hi:[1,0,1]
	v_pk_fma_f32 v[32:33], v[76:77], s[60:61], v[32:33] op_sel_hi:[1,0,1]
	v_pk_fma_f32 v[30:31], v[74:75], s[60:61], v[30:31] op_sel_hi:[1,0,1]
	v_pk_fma_f32 v[36:37], v[76:77], s[62:63], v[36:37] op_sel_hi:[1,0,1]
	v_pk_fma_f32 v[34:35], v[74:75], s[62:63], v[34:35] op_sel_hi:[1,0,1]
	v_pk_fma_f32 v[40:41], v[76:77], s[64:65], v[40:41] op_sel_hi:[1,0,1]
	v_pk_fma_f32 v[38:39], v[74:75], s[64:65], v[38:39] op_sel_hi:[1,0,1]
	v_pk_fma_f32 v[44:45], v[76:77], s[66:67], v[44:45] op_sel_hi:[1,0,1]
	v_pk_fma_f32 v[42:43], v[74:75], s[66:67], v[42:43] op_sel_hi:[1,0,1]
	v_pk_fma_f32 v[52:53], v[76:77], s[68:69], v[52:53] op_sel_hi:[1,0,1]
	v_pk_fma_f32 v[50:51], v[74:75], s[68:69], v[50:51] op_sel_hi:[1,0,1]
	v_pk_fma_f32 v[56:57], v[76:77], s[70:71], v[56:57] op_sel_hi:[1,0,1]
	v_pk_fma_f32 v[54:55], v[74:75], s[70:71], v[54:55] op_sel_hi:[1,0,1]
	v_pk_fma_f32 v[60:61], v[76:77], s[72:73], v[60:61] op_sel_hi:[1,0,1]
	v_pk_fma_f32 v[58:59], v[74:75], s[72:73], v[58:59] op_sel_hi:[1,0,1]
	v_readlane_b32 s56, v1, s7
	v_readlane_b32 s58, v104, s7
	v_readlane_b32 s60, v105, s7
	v_readlane_b32 s62, v106, s7
	v_readlane_b32 s64, v107, s7
	v_readlane_b32 s66, v108, s7
	v_readlane_b32 s68, v109, s7
	v_readlane_b32 s70, v110, s7
	v_readlane_b32 s72, v111, s7
	s_add_i32 s7, s6, 8
	s_waitcnt vmcnt(8)
	v_pk_fma_f32 v[24:25], v[72:73], s[56:57], v[24:25] op_sel_hi:[1,0,1]
	v_pk_fma_f32 v[22:23], v[70:71], s[56:57], v[22:23] op_sel_hi:[1,0,1]
	v_pk_fma_f32 v[28:29], v[72:73], s[58:59], v[28:29] op_sel_hi:[1,0,1]
	v_pk_fma_f32 v[26:27], v[70:71], s[58:59], v[26:27] op_sel_hi:[1,0,1]
	v_pk_fma_f32 v[32:33], v[72:73], s[60:61], v[32:33] op_sel_hi:[1,0,1]
	v_pk_fma_f32 v[30:31], v[70:71], s[60:61], v[30:31] op_sel_hi:[1,0,1]
	v_pk_fma_f32 v[36:37], v[72:73], s[62:63], v[36:37] op_sel_hi:[1,0,1]
	v_pk_fma_f32 v[34:35], v[70:71], s[62:63], v[34:35] op_sel_hi:[1,0,1]
	v_pk_fma_f32 v[40:41], v[72:73], s[64:65], v[40:41] op_sel_hi:[1,0,1]
	v_pk_fma_f32 v[38:39], v[70:71], s[64:65], v[38:39] op_sel_hi:[1,0,1]
	v_pk_fma_f32 v[44:45], v[72:73], s[66:67], v[44:45] op_sel_hi:[1,0,1]
	v_pk_fma_f32 v[42:43], v[70:71], s[66:67], v[42:43] op_sel_hi:[1,0,1]
	v_pk_fma_f32 v[52:53], v[72:73], s[68:69], v[52:53] op_sel_hi:[1,0,1]
	v_pk_fma_f32 v[50:51], v[70:71], s[68:69], v[50:51] op_sel_hi:[1,0,1]
	v_pk_fma_f32 v[56:57], v[72:73], s[70:71], v[56:57] op_sel_hi:[1,0,1]
	v_pk_fma_f32 v[54:55], v[70:71], s[70:71], v[54:55] op_sel_hi:[1,0,1]
	v_pk_fma_f32 v[60:61], v[72:73], s[72:73], v[60:61] op_sel_hi:[1,0,1]
	v_pk_fma_f32 v[58:59], v[70:71], s[72:73], v[58:59] op_sel_hi:[1,0,1]
	v_readlane_b32 s56, v1, s7
	v_readlane_b32 s58, v104, s7
	v_readlane_b32 s60, v105, s7
	v_readlane_b32 s62, v106, s7
	v_readlane_b32 s64, v107, s7
	v_readlane_b32 s66, v108, s7
	v_readlane_b32 s68, v109, s7
	v_readlane_b32 s70, v110, s7
	v_readlane_b32 s72, v111, s7
	s_add_i32 s7, s6, 9
	s_waitcnt vmcnt(7)
	v_pk_fma_f32 v[24:25], v[68:69], s[56:57], v[24:25] op_sel_hi:[1,0,1]
	v_pk_fma_f32 v[22:23], v[66:67], s[56:57], v[22:23] op_sel_hi:[1,0,1]
	v_pk_fma_f32 v[28:29], v[68:69], s[58:59], v[28:29] op_sel_hi:[1,0,1]
	v_pk_fma_f32 v[26:27], v[66:67], s[58:59], v[26:27] op_sel_hi:[1,0,1]
	v_pk_fma_f32 v[32:33], v[68:69], s[60:61], v[32:33] op_sel_hi:[1,0,1]
	v_pk_fma_f32 v[30:31], v[66:67], s[60:61], v[30:31] op_sel_hi:[1,0,1]
	v_pk_fma_f32 v[36:37], v[68:69], s[62:63], v[36:37] op_sel_hi:[1,0,1]
	v_pk_fma_f32 v[34:35], v[66:67], s[62:63], v[34:35] op_sel_hi:[1,0,1]
	v_pk_fma_f32 v[40:41], v[68:69], s[64:65], v[40:41] op_sel_hi:[1,0,1]
	v_pk_fma_f32 v[38:39], v[66:67], s[64:65], v[38:39] op_sel_hi:[1,0,1]
	v_pk_fma_f32 v[44:45], v[68:69], s[66:67], v[44:45] op_sel_hi:[1,0,1]
	v_pk_fma_f32 v[42:43], v[66:67], s[66:67], v[42:43] op_sel_hi:[1,0,1]
	v_pk_fma_f32 v[52:53], v[68:69], s[68:69], v[52:53] op_sel_hi:[1,0,1]
	v_pk_fma_f32 v[50:51], v[66:67], s[68:69], v[50:51] op_sel_hi:[1,0,1]
	v_pk_fma_f32 v[56:57], v[68:69], s[70:71], v[56:57] op_sel_hi:[1,0,1]
	v_pk_fma_f32 v[54:55], v[66:67], s[70:71], v[54:55] op_sel_hi:[1,0,1]
	v_pk_fma_f32 v[60:61], v[68:69], s[72:73], v[60:61] op_sel_hi:[1,0,1]
	v_pk_fma_f32 v[58:59], v[66:67], s[72:73], v[58:59] op_sel_hi:[1,0,1]
	v_readlane_b32 s56, v1, s7
	v_readlane_b32 s58, v104, s7
	v_readlane_b32 s60, v105, s7
	v_readlane_b32 s62, v106, s7
	v_readlane_b32 s64, v107, s7
	v_readlane_b32 s66, v108, s7
	v_readlane_b32 s68, v109, s7
	v_readlane_b32 s70, v110, s7
	v_readlane_b32 s72, v111, s7
	s_add_i32 s7, s6, 10
	s_waitcnt vmcnt(6)
	v_pk_fma_f32 v[24:25], v[64:65], s[56:57], v[24:25] op_sel_hi:[1,0,1]
	v_pk_fma_f32 v[22:23], v[62:63], s[56:57], v[22:23] op_sel_hi:[1,0,1]
	v_pk_fma_f32 v[28:29], v[64:65], s[58:59], v[28:29] op_sel_hi:[1,0,1]
	v_pk_fma_f32 v[26:27], v[62:63], s[58:59], v[26:27] op_sel_hi:[1,0,1]
	v_pk_fma_f32 v[32:33], v[64:65], s[60:61], v[32:33] op_sel_hi:[1,0,1]
	v_pk_fma_f32 v[30:31], v[62:63], s[60:61], v[30:31] op_sel_hi:[1,0,1]
	v_pk_fma_f32 v[36:37], v[64:65], s[62:63], v[36:37] op_sel_hi:[1,0,1]
	v_pk_fma_f32 v[34:35], v[62:63], s[62:63], v[34:35] op_sel_hi:[1,0,1]
	v_pk_fma_f32 v[40:41], v[64:65], s[64:65], v[40:41] op_sel_hi:[1,0,1]
	v_pk_fma_f32 v[38:39], v[62:63], s[64:65], v[38:39] op_sel_hi:[1,0,1]
	v_pk_fma_f32 v[44:45], v[64:65], s[66:67], v[44:45] op_sel_hi:[1,0,1]
	v_pk_fma_f32 v[42:43], v[62:63], s[66:67], v[42:43] op_sel_hi:[1,0,1]
	v_pk_fma_f32 v[52:53], v[64:65], s[68:69], v[52:53] op_sel_hi:[1,0,1]
	v_pk_fma_f32 v[50:51], v[62:63], s[68:69], v[50:51] op_sel_hi:[1,0,1]
	v_pk_fma_f32 v[56:57], v[64:65], s[70:71], v[56:57] op_sel_hi:[1,0,1]
	v_pk_fma_f32 v[54:55], v[62:63], s[70:71], v[54:55] op_sel_hi:[1,0,1]
	v_pk_fma_f32 v[60:61], v[64:65], s[72:73], v[60:61] op_sel_hi:[1,0,1]
	v_pk_fma_f32 v[58:59], v[62:63], s[72:73], v[58:59] op_sel_hi:[1,0,1]
	v_readlane_b32 s56, v1, s7
	v_readlane_b32 s58, v104, s7
	v_readlane_b32 s60, v105, s7
	v_readlane_b32 s62, v106, s7
	v_readlane_b32 s64, v107, s7
	v_readlane_b32 s66, v108, s7
	v_readlane_b32 s68, v109, s7
	v_readlane_b32 s70, v110, s7
	v_readlane_b32 s72, v111, s7
	s_add_i32 s7, s6, 11
	s_waitcnt vmcnt(5)
	v_pk_fma_f32 v[24:25], v[48:49], s[56:57], v[24:25] op_sel_hi:[1,0,1]
	v_pk_fma_f32 v[22:23], v[46:47], s[56:57], v[22:23] op_sel_hi:[1,0,1]
	v_pk_fma_f32 v[28:29], v[48:49], s[58:59], v[28:29] op_sel_hi:[1,0,1]
	v_pk_fma_f32 v[26:27], v[46:47], s[58:59], v[26:27] op_sel_hi:[1,0,1]
	v_pk_fma_f32 v[32:33], v[48:49], s[60:61], v[32:33] op_sel_hi:[1,0,1]
	v_pk_fma_f32 v[30:31], v[46:47], s[60:61], v[30:31] op_sel_hi:[1,0,1]
	v_pk_fma_f32 v[36:37], v[48:49], s[62:63], v[36:37] op_sel_hi:[1,0,1]
	v_pk_fma_f32 v[34:35], v[46:47], s[62:63], v[34:35] op_sel_hi:[1,0,1]
	v_pk_fma_f32 v[40:41], v[48:49], s[64:65], v[40:41] op_sel_hi:[1,0,1]
	v_pk_fma_f32 v[38:39], v[46:47], s[64:65], v[38:39] op_sel_hi:[1,0,1]
	v_pk_fma_f32 v[44:45], v[48:49], s[66:67], v[44:45] op_sel_hi:[1,0,1]
	v_pk_fma_f32 v[42:43], v[46:47], s[66:67], v[42:43] op_sel_hi:[1,0,1]
	v_pk_fma_f32 v[52:53], v[48:49], s[68:69], v[52:53] op_sel_hi:[1,0,1]
	v_pk_fma_f32 v[50:51], v[46:47], s[68:69], v[50:51] op_sel_hi:[1,0,1]
	v_pk_fma_f32 v[56:57], v[48:49], s[70:71], v[56:57] op_sel_hi:[1,0,1]
	v_pk_fma_f32 v[54:55], v[46:47], s[70:71], v[54:55] op_sel_hi:[1,0,1]
	v_pk_fma_f32 v[48:49], v[48:49], s[72:73], v[60:61] op_sel_hi:[1,0,1]
	v_pk_fma_f32 v[46:47], v[46:47], s[72:73], v[58:59] op_sel_hi:[1,0,1]
	v_readlane_b32 s56, v1, s7
	v_readlane_b32 s58, v104, s7
	v_readlane_b32 s60, v105, s7
	v_readlane_b32 s62, v106, s7
	v_readlane_b32 s64, v107, s7
	v_readlane_b32 s66, v108, s7
	v_readlane_b32 s68, v109, s7
	v_readlane_b32 s70, v110, s7
	v_readlane_b32 s72, v111, s7
	s_add_i32 s7, s6, 12
	s_waitcnt vmcnt(4)
	v_pk_fma_f32 v[24:25], v[20:21], s[56:57], v[24:25] op_sel_hi:[1,0,1]
	v_pk_fma_f32 v[22:23], v[18:19], s[56:57], v[22:23] op_sel_hi:[1,0,1]
	v_pk_fma_f32 v[28:29], v[20:21], s[58:59], v[28:29] op_sel_hi:[1,0,1]
	v_pk_fma_f32 v[26:27], v[18:19], s[58:59], v[26:27] op_sel_hi:[1,0,1]
	v_pk_fma_f32 v[32:33], v[20:21], s[60:61], v[32:33] op_sel_hi:[1,0,1]
	v_pk_fma_f32 v[30:31], v[18:19], s[60:61], v[30:31] op_sel_hi:[1,0,1]
	v_pk_fma_f32 v[36:37], v[20:21], s[62:63], v[36:37] op_sel_hi:[1,0,1]
	v_pk_fma_f32 v[34:35], v[18:19], s[62:63], v[34:35] op_sel_hi:[1,0,1]
	v_pk_fma_f32 v[40:41], v[20:21], s[64:65], v[40:41] op_sel_hi:[1,0,1]
	v_pk_fma_f32 v[38:39], v[18:19], s[64:65], v[38:39] op_sel_hi:[1,0,1]
	v_pk_fma_f32 v[44:45], v[20:21], s[66:67], v[44:45] op_sel_hi:[1,0,1]
	v_pk_fma_f32 v[42:43], v[18:19], s[66:67], v[42:43] op_sel_hi:[1,0,1]
	v_pk_fma_f32 v[52:53], v[20:21], s[68:69], v[52:53] op_sel_hi:[1,0,1]
	v_pk_fma_f32 v[50:51], v[18:19], s[68:69], v[50:51] op_sel_hi:[1,0,1]
	v_pk_fma_f32 v[56:57], v[20:21], s[70:71], v[56:57] op_sel_hi:[1,0,1]
	v_pk_fma_f32 v[54:55], v[18:19], s[70:71], v[54:55] op_sel_hi:[1,0,1]
	v_pk_fma_f32 v[20:21], v[20:21], s[72:73], v[48:49] op_sel_hi:[1,0,1]
	v_pk_fma_f32 v[18:19], v[18:19], s[72:73], v[46:47] op_sel_hi:[1,0,1]
	v_readlane_b32 s56, v1, s7
	v_readlane_b32 s58, v104, s7
	v_readlane_b32 s60, v105, s7
	v_readlane_b32 s62, v106, s7
	v_readlane_b32 s64, v107, s7
	v_readlane_b32 s66, v108, s7
	v_readlane_b32 s68, v109, s7
	v_readlane_b32 s70, v110, s7
	v_readlane_b32 s72, v111, s7
	s_add_i32 s7, s6, 13
	s_waitcnt vmcnt(3)
	v_pk_fma_f32 v[24:25], v[16:17], s[56:57], v[24:25] op_sel_hi:[1,0,1]
	v_pk_fma_f32 v[22:23], v[14:15], s[56:57], v[22:23] op_sel_hi:[1,0,1]
	v_pk_fma_f32 v[28:29], v[16:17], s[58:59], v[28:29] op_sel_hi:[1,0,1]
	v_pk_fma_f32 v[26:27], v[14:15], s[58:59], v[26:27] op_sel_hi:[1,0,1]
	v_pk_fma_f32 v[32:33], v[16:17], s[60:61], v[32:33] op_sel_hi:[1,0,1]
	v_pk_fma_f32 v[30:31], v[14:15], s[60:61], v[30:31] op_sel_hi:[1,0,1]
	v_pk_fma_f32 v[36:37], v[16:17], s[62:63], v[36:37] op_sel_hi:[1,0,1]
	v_pk_fma_f32 v[34:35], v[14:15], s[62:63], v[34:35] op_sel_hi:[1,0,1]
	v_pk_fma_f32 v[40:41], v[16:17], s[64:65], v[40:41] op_sel_hi:[1,0,1]
	v_pk_fma_f32 v[38:39], v[14:15], s[64:65], v[38:39] op_sel_hi:[1,0,1]
	v_pk_fma_f32 v[44:45], v[16:17], s[66:67], v[44:45] op_sel_hi:[1,0,1]
	v_pk_fma_f32 v[42:43], v[14:15], s[66:67], v[42:43] op_sel_hi:[1,0,1]
	v_pk_fma_f32 v[46:47], v[16:17], s[68:69], v[52:53] op_sel_hi:[1,0,1]
	v_pk_fma_f32 v[48:49], v[14:15], s[68:69], v[50:51] op_sel_hi:[1,0,1]
	v_pk_fma_f32 v[50:51], v[16:17], s[70:71], v[56:57] op_sel_hi:[1,0,1]
	v_pk_fma_f32 v[52:53], v[14:15], s[70:71], v[54:55] op_sel_hi:[1,0,1]
	v_pk_fma_f32 v[16:17], v[16:17], s[72:73], v[20:21] op_sel_hi:[1,0,1]
	v_pk_fma_f32 v[14:15], v[14:15], s[72:73], v[18:19] op_sel_hi:[1,0,1]
	v_readlane_b32 s56, v1, s7
	v_readlane_b32 s58, v104, s7
	v_readlane_b32 s60, v105, s7
	v_readlane_b32 s62, v106, s7
	v_readlane_b32 s64, v107, s7
	v_readlane_b32 s66, v108, s7
	v_readlane_b32 s68, v109, s7
	v_readlane_b32 s70, v110, s7
	v_readlane_b32 s72, v111, s7
	s_add_i32 s7, s6, 14
	s_waitcnt vmcnt(2)
	v_pk_fma_f32 v[18:19], v[12:13], s[56:57], v[24:25] op_sel_hi:[1,0,1]
	v_pk_fma_f32 v[20:21], v[10:11], s[56:57], v[22:23] op_sel_hi:[1,0,1]
	v_pk_fma_f32 v[22:23], v[12:13], s[58:59], v[28:29] op_sel_hi:[1,0,1]
	v_pk_fma_f32 v[24:25], v[10:11], s[58:59], v[26:27] op_sel_hi:[1,0,1]
	v_pk_fma_f32 v[26:27], v[12:13], s[60:61], v[32:33] op_sel_hi:[1,0,1]
	v_pk_fma_f32 v[28:29], v[10:11], s[60:61], v[30:31] op_sel_hi:[1,0,1]
	v_pk_fma_f32 v[30:31], v[12:13], s[62:63], v[36:37] op_sel_hi:[1,0,1]
	v_pk_fma_f32 v[32:33], v[10:11], s[62:63], v[34:35] op_sel_hi:[1,0,1]
	v_pk_fma_f32 v[34:35], v[12:13], s[64:65], v[40:41] op_sel_hi:[1,0,1]
	v_pk_fma_f32 v[36:37], v[10:11], s[64:65], v[38:39] op_sel_hi:[1,0,1]
	v_pk_fma_f32 v[38:39], v[12:13], s[66:67], v[44:45] op_sel_hi:[1,0,1]
	v_pk_fma_f32 v[40:41], v[10:11], s[66:67], v[42:43] op_sel_hi:[1,0,1]
	v_pk_fma_f32 v[42:43], v[12:13], s[68:69], v[46:47] op_sel_hi:[1,0,1]
	v_pk_fma_f32 v[44:45], v[10:11], s[68:69], v[48:49] op_sel_hi:[1,0,1]
	v_pk_fma_f32 v[46:47], v[12:13], s[70:71], v[50:51] op_sel_hi:[1,0,1]
	v_pk_fma_f32 v[48:49], v[10:11], s[70:71], v[52:53] op_sel_hi:[1,0,1]
	v_pk_fma_f32 v[12:13], v[12:13], s[72:73], v[16:17] op_sel_hi:[1,0,1]
	v_pk_fma_f32 v[10:11], v[10:11], s[72:73], v[14:15] op_sel_hi:[1,0,1]
	v_readlane_b32 s56, v1, s7
	v_readlane_b32 s58, v104, s7
	v_readlane_b32 s60, v105, s7
	v_readlane_b32 s62, v106, s7
	v_readlane_b32 s64, v107, s7
	v_readlane_b32 s66, v108, s7
	v_readlane_b32 s68, v109, s7
	v_readlane_b32 s70, v110, s7
	v_readlane_b32 s72, v111, s7
	s_add_i32 s7, s6, 15
	s_waitcnt vmcnt(1)
	v_pk_fma_f32 v[14:15], v[8:9], s[56:57], v[18:19] op_sel_hi:[1,0,1]
	v_pk_fma_f32 v[16:17], v[6:7], s[56:57], v[20:21] op_sel_hi:[1,0,1]
	v_pk_fma_f32 v[18:19], v[8:9], s[58:59], v[22:23] op_sel_hi:[1,0,1]
	v_pk_fma_f32 v[20:21], v[6:7], s[58:59], v[24:25] op_sel_hi:[1,0,1]
	v_pk_fma_f32 v[50:51], v[8:9], s[60:61], v[26:27] op_sel_hi:[1,0,1]
	v_pk_fma_f32 v[52:53], v[6:7], s[60:61], v[28:29] op_sel_hi:[1,0,1]
	v_pk_fma_f32 v[54:55], v[8:9], s[62:63], v[30:31] op_sel_hi:[1,0,1]
	v_pk_fma_f32 v[56:57], v[6:7], s[62:63], v[32:33] op_sel_hi:[1,0,1]
	v_pk_fma_f32 v[58:59], v[8:9], s[64:65], v[34:35] op_sel_hi:[1,0,1]
	v_pk_fma_f32 v[60:61], v[6:7], s[64:65], v[36:37] op_sel_hi:[1,0,1]
	v_pk_fma_f32 v[62:63], v[8:9], s[66:67], v[38:39] op_sel_hi:[1,0,1]
	v_pk_fma_f32 v[64:65], v[6:7], s[66:67], v[40:41] op_sel_hi:[1,0,1]
	v_pk_fma_f32 v[66:67], v[8:9], s[68:69], v[42:43] op_sel_hi:[1,0,1]
	v_pk_fma_f32 v[68:69], v[6:7], s[68:69], v[44:45] op_sel_hi:[1,0,1]
	v_pk_fma_f32 v[46:47], v[8:9], s[70:71], v[46:47] op_sel_hi:[1,0,1]
	v_pk_fma_f32 v[48:49], v[6:7], s[70:71], v[48:49] op_sel_hi:[1,0,1]
	v_pk_fma_f32 v[8:9], v[8:9], s[72:73], v[12:13] op_sel_hi:[1,0,1]
	v_pk_fma_f32 v[6:7], v[6:7], s[72:73], v[10:11] op_sel_hi:[1,0,1]
	v_readlane_b32 s56, v1, s7
	v_readlane_b32 s58, v104, s7
	v_readlane_b32 s60, v105, s7
	v_readlane_b32 s62, v106, s7
	v_readlane_b32 s64, v107, s7
	v_readlane_b32 s66, v108, s7
	v_readlane_b32 s68, v109, s7
	v_readlane_b32 s70, v110, s7
	v_readlane_b32 s72, v111, s7
	s_add_i32 s7, s6, 16
	s_waitcnt vmcnt(0)
	v_pk_fma_f32 v[24:25], v[4:5], s[56:57], v[14:15] op_sel_hi:[1,0,1]
	v_pk_fma_f32 v[22:23], v[2:3], s[56:57], v[16:17] op_sel_hi:[1,0,1]
	v_pk_fma_f32 v[28:29], v[4:5], s[58:59], v[18:19] op_sel_hi:[1,0,1]
	v_pk_fma_f32 v[26:27], v[2:3], s[58:59], v[20:21] op_sel_hi:[1,0,1]
	v_pk_fma_f32 v[32:33], v[4:5], s[60:61], v[50:51] op_sel_hi:[1,0,1]
	v_pk_fma_f32 v[30:31], v[2:3], s[60:61], v[52:53] op_sel_hi:[1,0,1]
	v_pk_fma_f32 v[36:37], v[4:5], s[62:63], v[54:55] op_sel_hi:[1,0,1]
	v_pk_fma_f32 v[34:35], v[2:3], s[62:63], v[56:57] op_sel_hi:[1,0,1]
	v_pk_fma_f32 v[40:41], v[4:5], s[64:65], v[58:59] op_sel_hi:[1,0,1]
	v_pk_fma_f32 v[38:39], v[2:3], s[64:65], v[60:61] op_sel_hi:[1,0,1]
	v_pk_fma_f32 v[44:45], v[4:5], s[66:67], v[62:63] op_sel_hi:[1,0,1]
	v_pk_fma_f32 v[42:43], v[2:3], s[66:67], v[64:65] op_sel_hi:[1,0,1]
	v_pk_fma_f32 v[52:53], v[4:5], s[68:69], v[66:67] op_sel_hi:[1,0,1]
	v_pk_fma_f32 v[50:51], v[2:3], s[68:69], v[68:69] op_sel_hi:[1,0,1]
	v_pk_fma_f32 v[56:57], v[4:5], s[70:71], v[46:47] op_sel_hi:[1,0,1]
	v_pk_fma_f32 v[54:55], v[2:3], s[70:71], v[48:49] op_sel_hi:[1,0,1]
	s_cmp_gt_u32 s6, 47
	v_pk_fma_f32 v[60:61], v[4:5], s[72:73], v[8:9] op_sel_hi:[1,0,1]
	v_pk_fma_f32 v[58:59], v[2:3], s[72:73], v[6:7] op_sel_hi:[1,0,1]
	s_mov_b64 s[8:9], 0x240000
	v_lshl_add_u64 v[100:101], v[100:101], 0, s[8:9]
	s_mov_b32 s6, s7
	s_cbranch_scc0 .LBB0_16
	s_add_i32 s5, s5, 1
	s_mov_b64 s[6:7], 0x900000
	s_cmp_eq_u32 s5, 8
	v_lshl_add_u64 v[98:99], v[98:99], 0, s[6:7]
	s_cbranch_scc0 .LBB0_15
	s_and_saveexec_b64 s[6:7], s[0:1]
	s_cbranch_execz .LBB0_20
	ds_write_b128 v103, v[22:25]
	ds_write_b128 v103, v[26:29] offset:576
	ds_write_b128 v103, v[30:33] offset:1152
	ds_write_b128 v103, v[34:37] offset:1728
	ds_write_b128 v103, v[38:41] offset:2304
	ds_write_b128 v103, v[42:45] offset:2880
	ds_write_b128 v103, v[50:53] offset:3456
	ds_write_b128 v103, v[54:57] offset:4032
	ds_write_b128 v103, v[58:61] offset:4608
